# K-split of phase B tail rebalanced: epilogue-owning CU takes 14 of 32 K-tiles, partner takes 18
# baseline (speedup 1.0000x reference)
;     __device__ __forceinline__ bool next(int i, Unit& u) const {
;         const int L = i * G + c; if (L >= 2688) return false; u.nt = 32;
;         if (L < 2304) { pg8::remap(L, 64, 36, u.pm, u.pn); u.pn += 12; if (u.pn >= 36) u.pn -= 36; u.aux = 0;
;              u.A = H + (size_t)u.pm * 256 * 2048 * 2; u.B = W + (size_t)(1536 + u.pn * 256) * 2048 * 2; }
;         else { pg8::remap(L - 2304, 6, 64, u.pm, u.pn); u.aux = 1; u.A = W + (size_t)u.pm * 256 * 2048 * 2; u.B = H + (size_t)u.pn * 256 * 2048 * 2; }
.Lks_nosplit:
	s_cmpk_gt_i32 s1, 0xa7f
	s_cselect_b64 s[6:7], -1, 0
	s_and_b64 vcc, exec, s[6:7]
	s_cbranch_vccnz .LBB0_1039
	s_cmpk_gt_i32 s1, 0x8ff
	s_mov_b64 s[22:23], -1
	s_cbranch_scc0 .LBB0_1037
	s_and_b32 s8, s1, 7
	s_add_i32 s9, s1, 0xf700
	s_mul_i32 s8, s8, 48
	s_bfe_u32 s9, s9, 0xd0003
	s_add_i32 s9, s9, s8
	s_and_b32 s8, s9, 0xffff
	s_mul_i32 s8, s8, 0xaaab
	s_lshr_b32 s8, s8, 18
	s_mul_i32 s10, s8, 6
	s_sub_i32 s9, s9, s10
	s_and_b32 s70, s9, 0xffff
	s_lshl_b64 s[10:11], s[70:71], 20
	v_readlane_b32 s9, v255, 6
	s_add_u32 s12, s9, s10
	v_readlane_b32 s9, v255, 7
	s_addc_u32 s13, s9, s11
	s_mov_b32 s9, s71
	s_lshl_b64 s[10:11], s[8:9], 20
	s_add_u32 s14, s28, s10
	s_addc_u32 s15, s29, s11
	s_mov_b64 s[22:23], 0
	s_mov_b32 s10, s70
	s_cmp_eq_u32 s98, 2
	s_cbranch_scc0 .Lks_noff
	s_add_u32 s12, s12, 0x700
	s_addc_u32 s13, s13, 0
	s_add_u32 s14, s14, 0x700
	s_addc_u32 s15, s15, 0

; #define PG8_SCHED __builtin_amdgcn_sched_barrier(0)
; template <class Epi, class Sched>
; __device__ __forceinline__ void gemm_phase(LAS unsigned char* lds_in, const int lda, const int ldb, const Sched& S, const Epi& E, const int WID) {
;     ...
;         for (int sg = 0; sg < (Epi::HAS_MID ? 3 : 1); ++sg) {
;         const int tb = Epi::HAS_MID ? (sg == 0 ? 0 : (sg == 1 ? 16 : 24)) : 0, te = Epi::HAS_MID ? (sg == 0 ? 16 : (sg == 1 ? 24 : nt)) : nt;
;         if constexpr (Epi::HAS_MID) { if (sg > 0) { PG8_SCHED; E.mid(acc, cur, tb, wr, wc, fr, fq); PG8_SCHED; } }
;         for (int t = tb; t < te; t += 2) {
;     ...
; #pragma unroll
;         for (int a = 0; a < 2; ++a)
; #pragma unroll
;             for (int b = 0; b < 2; ++b)
; #pragma unroll
;                 for (int m = 0; m < 4; ++m)
; #pragma unroll
;                     for (int n = 0; n < 2; ++n) acc[a][b][m][n] = (f32x4){0.f, 0.f, 0.f, 0.f};
;         cur = nxt; cA = nA; cB = nB; ++ui;
.LBB0_1039:
	s_add_u32 s18, s18, 0x80080
	s_addc_u32 s19, s19, 0
	s_add_u32 s1, s20, 0x100
	v_mov_b32_e32 v2, 0
	s_addc_u32 s11, s21, 0
	s_mov_b32 s70, -2
	s_cmp_eq_u32 s99, 0
	s_cselect_b32 s32, 28, 10
	s_cmp_eq_u32 s99, 2
	s_cselect_b32 s32, 14, s32
	v_mov_b32_e32 v3, v2
	v_mov_b32_e32 v4, v2
	v_mov_b32_e32 v5, v2
	v_mov_b32_e32 v6, v2
	v_mov_b32_e32 v7, v2
	v_mov_b32_e32 v8, v2
	v_mov_b32_e32 v9, v2
	v_mov_b32_e32 v10, v2
	v_mov_b32_e32 v11, v2
	v_mov_b32_e32 v12, v2
	v_mov_b32_e32 v13, v2
	v_mov_b32_e32 v14, v2
	v_mov_b32_e32 v15, v2
	v_mov_b32_e32 v16, v2
	v_mov_b32_e32 v17, v2
	v_mov_b32_e32 v18, v2
	v_mov_b32_e32 v19, v2
	v_mov_b32_e32 v20, v2
	v_mov_b32_e32 v21, v2
	v_mov_b32_e32 v22, v2
	v_mov_b32_e32 v23, v2
	v_mov_b32_e32 v24, v2
	v_mov_b32_e32 v25, v2
	v_mov_b32_e32 v26, v2
	v_mov_b32_e32 v27, v2
	v_mov_b32_e32 v28, v2
	v_mov_b32_e32 v29, v2
	v_mov_b32_e32 v30, v2
	v_mov_b32_e32 v31, v2
	v_mov_b32_e32 v32, v2
	v_mov_b32_e32 v33, v2
	v_mov_b32_e32 v66, v2
	v_mov_b32_e32 v67, v2
	v_mov_b32_e32 v68, v2
	v_mov_b32_e32 v69, v2
	v_mov_b32_e32 v70, v2
	v_mov_b32_e32 v71, v2
	v_mov_b32_e32 v72, v2
	v_mov_b32_e32 v73, v2
	v_mov_b32_e32 v74, v2
	v_mov_b32_e32 v75, v2
	v_mov_b32_e32 v76, v2
	v_mov_b32_e32 v77, v2
	v_mov_b32_e32 v78, v2
	v_mov_b32_e32 v79, v2
	v_mov_b32_e32 v80, v2
	v_mov_b32_e32 v81, v2
	v_mov_b32_e32 v82, v2
	v_mov_b32_e32 v83, v2
	v_mov_b32_e32 v84, v2
	v_mov_b32_e32 v85, v2
	v_mov_b32_e32 v86, v2
	v_mov_b32_e32 v87, v2
	v_mov_b32_e32 v88, v2
	v_mov_b32_e32 v89, v2
	v_mov_b32_e32 v90, v2
	v_mov_b32_e32 v91, v2
	v_mov_b32_e32 v92, v2
	v_mov_b32_e32 v93, v2
	v_mov_b32_e32 v94, v2
	v_mov_b32_e32 v95, v2
	v_mov_b32_e32 v96, v2
	v_mov_b32_e32 v97, v2
	v_mov_b32_e32 v34, v2
	v_mov_b32_e32 v35, v2
	v_mov_b32_e32 v36, v2
	v_mov_b32_e32 v37, v2
	v_mov_b32_e32 v38, v2
	v_mov_b32_e32 v39, v2
	v_mov_b32_e32 v40, v2
	v_mov_b32_e32 v41, v2
	v_mov_b32_e32 v42, v2
	v_mov_b32_e32 v43, v2
	v_mov_b32_e32 v44, v2
	v_mov_b32_e32 v45, v2
	v_mov_b32_e32 v46, v2
	v_mov_b32_e32 v47, v2
	v_mov_b32_e32 v48, v2
	v_mov_b32_e32 v49, v2
	v_mov_b32_e32 v50, v2
	v_mov_b32_e32 v51, v2
	v_mov_b32_e32 v52, v2
	v_mov_b32_e32 v53, v2
	v_mov_b32_e32 v54, v2
	v_mov_b32_e32 v55, v2
	v_mov_b32_e32 v56, v2
	v_mov_b32_e32 v57, v2
	v_mov_b32_e32 v58, v2
	v_mov_b32_e32 v59, v2
	v_mov_b32_e32 v60, v2
	v_mov_b32_e32 v61, v2
	v_mov_b32_e32 v62, v2
	v_mov_b32_e32 v63, v2
	v_mov_b32_e32 v64, v2
	v_mov_b32_e32 v65, v2
	v_mov_b32_e32 v98, v2
	v_mov_b32_e32 v99, v2
	v_mov_b32_e32 v100, v2
	v_mov_b32_e32 v101, v2
	v_mov_b32_e32 v102, v2
	v_mov_b32_e32 v103, v2
	v_mov_b32_e32 v104, v2
	v_mov_b32_e32 v105, v2
	v_mov_b32_e32 v106, v2
	v_mov_b32_e32 v107, v2
	v_mov_b32_e32 v108, v2
	v_mov_b32_e32 v109, v2
	v_mov_b32_e32 v110, v2
	v_mov_b32_e32 v111, v2
	v_mov_b32_e32 v112, v2
	v_mov_b32_e32 v113, v2
	v_mov_b32_e32 v114, v2
	v_mov_b32_e32 v115, v2
	v_mov_b32_e32 v116, v2
	v_mov_b32_e32 v117, v2
	v_mov_b32_e32 v118, v2
	v_mov_b32_e32 v119, v2
	v_mov_b32_e32 v120, v2
	v_mov_b32_e32 v121, v2
	v_mov_b32_e32 v122, v2
	v_mov_b32_e32 v123, v2
	v_mov_b32_e32 v124, v2
	v_mov_b32_e32 v125, v2
	v_mov_b32_e32 v126, v2
	v_mov_b32_e32 v127, v2
	v_mov_b32_e32 v128, v2
	v_mov_b32_e32 v129, v2
